# HGRN2 core: next-chunk LF/q prefetch loads issued inside the decay/exp chain as each row's registers die (counted vmcnt(32) for the V tile), scalar chunk bases
# baseline (speedup 1.0000x reference)
; #define GAS __attribute__((address_space(1)))
; template <int DK, int DVS, bool RET> ...
;     ...
;     const int kx = tid % DK, pg = tid / DK;
;     const GAS bf16_t* Qg = (const GAS bf16_t*)Q; const GAS bf16_t* Kg = (const GAS bf16_t*)Kp; const GAS float* LFg = (const GAS float*)LF; const GAS bf16_t* Vg = (const GAS bf16_t*)V;
;     ...
;     GLA_LOAD(0);
; __global__ void __launch_bounds__(512) mk_fwd(Params P) {
;     ...
;             for (int L = bid; L < 256; L += G) {
;                 const int slice = L & 3, dir = (L >> 2) & 1, hh = (L >> 3) & 7, bq = L >> 6;
;                 gla_unit<128, 32, false>(lds, bq, hh, dir, slice, Qb, nullptr, Vb, LF, dir ? OB : OF, 0.f, 1024, hh * 128 + slice * 32, tid);
.LBB0_52:
	s_bfe_i32 s36, s49, 0x10002
	s_bfe_u32 s63, s49, 0x10002
	s_ashr_i32 s40, s49, 6
	s_cmp_eq_u32 s63, 0
	s_cselect_b64 s[30:31], -1, 0
	s_and_b64 s[42:43], s[30:31], exec
	s_mov_b32 s42, 0x18b69000
	s_cselect_b32 s42, s42, 0x1ad69000
	s_add_u32 s56, s0, s42
	s_addc_u32 s57, s1, 0
	s_lshl_b32 s42, s49, 4
	s_and_b32 s66, s42, 0x380
	s_lshl_b32 s42, s49, 5
	s_and_b32 s42, s42, 0x60
	s_mov_b32 s41, 0
	s_or_b32 s62, s66, s42
	s_mul_hi_i32 s43, s40, 0x1100
	s_mul_i32 s42, s40, 0x1100
	s_and_b32 s40, s36, 0xc0
	s_or_b64 s[44:45], s[40:41], s[42:43]
	s_lshl_b32 s36, s63, 12
	s_add_u32 s36, s3, s36
	v_sub_u32_e32 v28, 63, v79
	s_addc_u32 s40, s48, 0
	s_lshl_b32 s63, s66, 2
	v_cndmask_b32_e64 v28, v28, v79, s[30:31]
	s_add_u32 s64, s36, s63
	v_ashrrev_i32_e32 v29, 31, v28
	s_addc_u32 s65, s40, 0
	s_lshl_b32 s36, s66, 1
	v_lshl_add_u64 v[30:31], s[44:45], 0, v[28:29]
	v_lshl_add_u64 v[24:25], v[12:13], 0, s[36:37]
	v_lshlrev_b64 v[32:33], 13, v[30:31]
	v_lshlrev_b64 v[30:31], 11, v[30:31]
	v_sub_u32_e32 v0, 63, v77
	v_lshl_add_u64 v[34:35], v[24:25], 0, v[30:31]
	v_sub_u32_e32 v30, 63, v80
	v_cndmask_b32_e64 v20, v0, v77, s[30:31]
	v_sub_u32_e32 v4, 63, v78
	v_cndmask_b32_e64 v30, v30, v80, s[30:31]
	v_ashrrev_i32_e32 v21, 31, v20
	v_cndmask_b32_e64 v26, v4, v78, s[30:31]
	v_ashrrev_i32_e32 v31, 31, v30
	v_lshl_add_u64 v[0:1], s[44:45], 0, v[20:21]
	v_ashrrev_i32_e32 v27, 31, v26
	v_lshl_add_u64 v[36:37], s[44:45], 0, v[30:31]
	v_lshl_add_u64 v[22:23], v[10:11], 2, s[64:65]
	v_lshlrev_b64 v[2:3], 13, v[0:1]
	v_lshl_add_u64 v[4:5], s[44:45], 0, v[26:27]
	v_lshlrev_b64 v[38:39], 13, v[36:37]
	v_lshlrev_b64 v[36:37], 11, v[36:37]
	v_readlane_b32 s59, v253, 62
	v_readlane_b32 s51, v254, 0
	v_readlane_b32 s47, v254, 2
	s_mov_b32 s50, s37
	v_readlane_b32 s46, v253, 63
	v_readlane_b32 s61, v254, 1
	v_readlane_b32 s60, v254, 3
	v_lshl_add_u64 v[2:3], v[22:23], 0, v[2:3]
	v_lshlrev_b64 v[0:1], 11, v[0:1]
	v_lshlrev_b64 v[6:7], 13, v[4:5]
	v_lshlrev_b64 v[4:5], 11, v[4:5]
	v_lshl_add_u64 v[36:37], v[24:25], 0, v[36:37]
	v_lshl_add_u64 v[0:1], v[24:25], 0, v[0:1]
	v_lshl_add_u64 v[6:7], v[22:23], 0, v[6:7]
	v_lshl_add_u64 v[4:5], v[24:25], 0, v[4:5]
	v_lshl_add_u64 v[32:33], v[22:23], 0, v[32:33]
	v_lshl_add_u64 v[38:39], v[22:23], 0, v[38:39]
	global_load_dword v132, v[2:3], off
	global_load_ushort v133, v[0:1], off
	global_load_dword v134, v[6:7], off
	global_load_ushort v135, v[4:5], off
	global_load_dword v136, v[32:33], off
	global_load_ushort v137, v[34:35], off
	global_load_dword v138, v[38:39], off
	global_load_ushort v139, v[36:37], off
	v_sub_u32_e32 v36, 63, v83
	v_cndmask_b32_e64 v36, v36, v83, s[30:31]
	v_ashrrev_i32_e32 v37, 31, v36
	v_lshl_add_u64 v[38:39], s[44:45], 0, v[36:37]
	v_lshlrev_b64 v[40:41], 13, v[38:39]
	v_lshlrev_b64 v[38:39], 11, v[38:39]
	v_sub_u32_e32 v0, 63, v81
	v_lshl_add_u64 v[42:43], v[24:25], 0, v[38:39]
	v_sub_u32_e32 v38, 63, v84
	v_cndmask_b32_e64 v32, v0, v81, s[30:31]
	v_sub_u32_e32 v4, 63, v82
	v_cndmask_b32_e64 v38, v38, v84, s[30:31]
	v_ashrrev_i32_e32 v33, 31, v32
	v_cndmask_b32_e64 v34, v4, v82, s[30:31]
	v_ashrrev_i32_e32 v39, 31, v38
	v_lshl_add_u64 v[0:1], s[44:45], 0, v[32:33]
	v_ashrrev_i32_e32 v35, 31, v34
	v_lshl_add_u64 v[44:45], s[44:45], 0, v[38:39]
	v_lshlrev_b64 v[2:3], 13, v[0:1]
	v_lshl_add_u64 v[4:5], s[44:45], 0, v[34:35]
	v_lshlrev_b64 v[46:47], 13, v[44:45]
	v_lshlrev_b64 v[44:45], 11, v[44:45]
	v_lshl_add_u64 v[2:3], v[22:23], 0, v[2:3]
	v_lshlrev_b64 v[0:1], 11, v[0:1]
	v_lshlrev_b64 v[6:7], 13, v[4:5]
	v_lshlrev_b64 v[4:5], 11, v[4:5]
	v_lshl_add_u64 v[44:45], v[24:25], 0, v[44:45]
	v_lshl_add_u64 v[0:1], v[24:25], 0, v[0:1]
	v_lshl_add_u64 v[6:7], v[22:23], 0, v[6:7]
	v_lshl_add_u64 v[4:5], v[24:25], 0, v[4:5]
	v_lshl_add_u64 v[40:41], v[22:23], 0, v[40:41]
	v_lshl_add_u64 v[46:47], v[22:23], 0, v[46:47]
	global_load_dword v140, v[2:3], off
	global_load_ushort v141, v[0:1], off
	global_load_dword v142, v[6:7], off
	global_load_ushort v143, v[4:5], off
	global_load_dword v147, v[40:41], off
	global_load_ushort v150, v[42:43], off
	global_load_dword v151, v[46:47], off
	global_load_ushort v162, v[44:45], off
	v_sub_u32_e32 v44, 63, v87
	v_cndmask_b32_e64 v44, v44, v87, s[30:31]
	v_ashrrev_i32_e32 v45, 31, v44
	v_lshl_add_u64 v[46:47], s[44:45], 0, v[44:45]
	v_lshlrev_b64 v[48:49], 13, v[46:47]
	v_lshlrev_b64 v[46:47], 11, v[46:47]
	v_sub_u32_e32 v0, 63, v85
	v_lshl_add_u64 v[50:51], v[24:25], 0, v[46:47]
	v_sub_u32_e32 v46, 63, v88
	v_cndmask_b32_e64 v40, v0, v85, s[30:31]
	v_sub_u32_e32 v4, 63, v86
	v_cndmask_b32_e64 v46, v46, v88, s[30:31]
	v_ashrrev_i32_e32 v41, 31, v40
	v_cndmask_b32_e64 v42, v4, v86, s[30:31]
	v_ashrrev_i32_e32 v47, 31, v46
	v_lshl_add_u64 v[0:1], s[44:45], 0, v[40:41]
	v_ashrrev_i32_e32 v43, 31, v42
	v_lshl_add_u64 v[52:53], s[44:45], 0, v[46:47]
	v_lshlrev_b64 v[2:3], 13, v[0:1]
	v_lshl_add_u64 v[4:5], s[44:45], 0, v[42:43]
	v_lshlrev_b64 v[54:55], 13, v[52:53]
	v_lshlrev_b64 v[52:53], 11, v[52:53]
	v_lshl_add_u64 v[2:3], v[22:23], 0, v[2:3]
	v_lshlrev_b64 v[0:1], 11, v[0:1]
	v_lshlrev_b64 v[6:7], 13, v[4:5]
	v_lshlrev_b64 v[4:5], 11, v[4:5]
	v_lshl_add_u64 v[52:53], v[24:25], 0, v[52:53]
	v_lshl_add_u64 v[0:1], v[24:25], 0, v[0:1]
	v_lshl_add_u64 v[6:7], v[22:23], 0, v[6:7]
	v_lshl_add_u64 v[4:5], v[24:25], 0, v[4:5]
	v_lshl_add_u64 v[48:49], v[22:23], 0, v[48:49]
	v_lshl_add_u64 v[54:55], v[22:23], 0, v[54:55]
	global_load_dword v210, v[2:3], off
	global_load_ushort v217, v[0:1], off
	global_load_dword v220, v[6:7], off
	global_load_ushort v221, v[4:5], off
	global_load_dword v222, v[48:49], off
	global_load_ushort v223, v[50:51], off
	global_load_dword v224, v[54:55], off
; #define GAS __attribute__((address_space(1)))
; template <int DK, int DVS, bool RET> ...
;     ...
;     const int wid = tid >> 6, lane = tid & 63, l16 = lane & 15, quad = lane >> 4;
;     const int tr = wid >> 1, tv = wid / WPV, kt0 = (wid % WPV) * TPW;
;     const int vtr = (int)aVI + (8 * quad + (l16 >> 2)) * (LV * 2) + 8 * (lane & 3);
;     const int ktr = (int)aKD + (8 * quad + (l16 >> 2)) * (LK * 2) + 8 * (lane & 3);
;     ...
;     f32x4 st[TPW];
; #pragma unroll
;     for (int t = 0; t < TPW; ++t) st[t] = (f32x4){0.f, 0.f, 0.f, 0.f};
;     ...
;     typedef short vvec_t __attribute__((ext_vector_type(VPT)));
;     constexpr int NQV = RET ? 4 : 1, NLC = RET ? 1 : PPT;
;     bf16x8 qv[NQV], kv[NQV]; float lc[NLC]; bf16_t qr[NLC]; vvec_t vraw;
;     const int kx = tid % DK, pg = tid / DK;
;     const GAS bf16_t* Qg = (const GAS bf16_t*)Q; const GAS bf16_t* Kg = (const GAS bf16_t*)Kp; const GAS float* LFg = (const GAS float*)LF; const GAS bf16_t* Vg = (const GAS bf16_t*)V;
;     ...
;     GLA_LOAD(0);
	global_load_ushort v225, v[52:53], off
	v_sub_u32_e32 v52, 63, v91
	v_cndmask_b32_e64 v52, v52, v91, s[30:31]
	v_ashrrev_i32_e32 v53, 31, v52
	v_lshl_add_u64 v[54:55], s[44:45], 0, v[52:53]
	v_sub_u32_e32 v0, 63, v89
	v_lshlrev_b64 v[56:57], 13, v[54:55]
	v_lshlrev_b64 v[54:55], 11, v[54:55]
	v_cndmask_b32_e64 v48, v0, v89, s[30:31]
	v_sub_u32_e32 v4, 63, v90
	v_lshl_add_u64 v[58:59], v[24:25], 0, v[54:55]
	v_sub_u32_e32 v54, 63, v92
	v_ashrrev_i32_e32 v49, 31, v48
	v_cndmask_b32_e64 v50, v4, v90, s[30:31]
	v_cndmask_b32_e64 v54, v54, v92, s[30:31]
	v_lshl_add_u64 v[0:1], s[44:45], 0, v[48:49]
	v_ashrrev_i32_e32 v51, 31, v50
	v_ashrrev_i32_e32 v55, 31, v54
	v_lshlrev_b64 v[2:3], 13, v[0:1]
	v_lshl_add_u64 v[4:5], s[44:45], 0, v[50:51]
	v_lshl_add_u64 v[60:61], s[44:45], 0, v[54:55]
	v_lshl_add_u64 v[2:3], v[22:23], 0, v[2:3]
	v_lshlrev_b64 v[0:1], 11, v[0:1]
	v_lshlrev_b64 v[6:7], 13, v[4:5]
	v_lshlrev_b64 v[4:5], 11, v[4:5]
	v_lshlrev_b64 v[62:63], 13, v[60:61]
	v_lshlrev_b64 v[60:61], 11, v[60:61]
	v_lshl_add_u64 v[0:1], v[24:25], 0, v[0:1]
	v_lshl_add_u64 v[6:7], v[22:23], 0, v[6:7]
	v_lshl_add_u64 v[4:5], v[24:25], 0, v[4:5]
	v_lshl_add_u64 v[56:57], v[22:23], 0, v[56:57]
	v_lshl_add_u64 v[62:63], v[22:23], 0, v[62:63]
	v_lshl_add_u64 v[60:61], v[24:25], 0, v[60:61]
	global_load_dword v226, v[2:3], off
	global_load_ushort v227, v[0:1], off
	global_load_dword v228, v[6:7], off
	global_load_ushort v229, v[4:5], off
	global_load_dword v230, v[56:57], off
	global_load_ushort v231, v[58:59], off
	global_load_dword v232, v[62:63], off
	global_load_ushort v233, v[60:61], off
	v_sub_u32_e32 v2, 63, v93
	s_lshl_b32 s36, s62, 1
	v_cndmask_b32_e64 v56, v2, v93, s[30:31]
	v_lshlrev_b32_e32 v2, 2, v10
	s_movk_i32 s40, 0x50
	s_add_u32 s44, s56, s36
	v_lshlrev_b32_e32 v1, 1, v9
	v_lshlrev_b32_e32 v0, 1, v8
	v_add_u32_e32 v153, s61, v2
	v_add_u32_e32 v154, s51, v2
	v_mul_lo_u32 v2, v93, s40
	s_addc_u32 s45, s57, 0
	v_add_u32_e32 v4, s50, v1
	v_add_u32_e32 v5, s60, v0
	v_add3_u32 v155, s59, v2, v14
	v_add3_u32 v156, s47, v96, v1
	v_add_u32_e32 v6, s60, v1
	v_add3_u32 v158, s46, v99, v1
	v_lshl_add_u64 v[2:3], s[44:45], 0, v[144:145]
	v_mov_b32_e32 v1, v145
	v_add_u32_e32 v64, s59, v76
	v_lshl_add_u64 v[60:61], v[2:3], 0, v[0:1]
	v_add_u32_e32 v0, s47, v101
	v_add_u32_e32 v2, v5, v102
	v_add_u32_e32 v3, v5, v104
	v_lshlrev_b32_e32 v5, 1, v18
	v_add_u32_e32 v157, v64, v15
	v_add_u32_e32 v159, v64, v100
	v_lshl_add_u32 v1, v8, 2, s51
	v_add_u32_e32 v163, s50, v5
	v_add_u32_e32 v164, s47, v5
	v_lshlrev_b32_e32 v5, 1, v95
	v_cndmask_b32_e64 v62, v251, v97, s[30:31]
	v_cndmask_b32_e64 v64, v252, v105, s[30:31]
	v_cndmask_b32_e64 v66, v198, v107, s[30:31]
	v_cndmask_b32_e64 v68, v114, v109, s[30:31]
	v_add_u32_e32 v211, v0, v102
	v_add_u32_e32 v212, v0, v104
	v_mov_b32_e32 v0, 0
	v_ashrrev_i32_e32 v57, 31, v56
	v_lshl_add_u64 v[58:59], v[16:17], 0, s[36:37]
	v_lshl_add_u32 v152, v146, 2, s61
	v_add_u32_e32 v160, s50, v117
	v_add_u32_e32 v161, s47, v117
	v_add_u32_e32 v165, s50, v118
	v_add_u32_e32 v166, s47, v118
	v_add_u32_e32 v167, s50, v119
	v_add_u32_e32 v168, s47, v119
	v_add_u32_e32 v169, s50, v120
	v_add_u32_e32 v170, s47, v120
	v_add_u32_e32 v171, s50, v121
	v_add_u32_e32 v172, s47, v121
	v_add_u32_e32 v173, s50, v122
	v_add_u32_e32 v174, s47, v122
	v_add_u32_e32 v175, s50, v123
	v_add_u32_e32 v176, s47, v123
	v_add_u32_e32 v177, s50, v124
	v_add_u32_e32 v178, s47, v124
	v_add_u32_e32 v179, s50, v125
	v_add_u32_e32 v180, s47, v125
	v_add_u32_e32 v181, s50, v126
	v_add_u32_e32 v182, s47, v126
	v_add_u32_e32 v183, s50, v127
	v_add_u32_e32 v184, s47, v127
	v_add_u32_e32 v185, s50, v128
	v_add_u32_e32 v199, s47, v128
	v_add_u32_e32 v200, s50, v129
	v_add_u32_e32 v201, s47, v129
	v_add_u32_e32 v202, s50, v130
	v_add_u32_e32 v203, s47, v130
	v_add_u32_e32 v204, s50, v131
	v_add_u32_e32 v205, s47, v131
	v_add3_u32 v206, s46, v19, v5
	v_add3_u32 v207, s46, v106, v5
	v_add3_u32 v208, s46, v108, v5
	v_add3_u32 v209, s46, v250, v5
	v_ashrrev_i32_e32 v63, 31, v62
	v_ashrrev_i32_e32 v65, 31, v64
	v_ashrrev_i32_e32 v67, 31, v66
	v_ashrrev_i32_e32 v69, 31, v68
	v_add_u32_e32 v213, v2, v103
	v_add_u32_e32 v214, v3, v103
	v_add_u32_e32 v215, v4, v94
	v_add_u32_e32 v216, v6, v98
	v_add_u32_e32 v218, v1, v115
	v_add_u32_e32 v219, v1, v116
	s_mov_b32 s36, s41
	v_mov_b32_e32 v1, v0
	v_mov_b32_e32 v2, v0
	v_mov_b32_e32 v3, v0
	v_mov_b32_e32 v4, v0
	v_mov_b32_e32 v5, v0
	v_mov_b32_e32 v6, v0
	v_mov_b32_e32 v7, v0
	v_mov_b32_e32 v71, v0
	v_mov_b32_e32 v72, v0
	v_mov_b32_e32 v73, v0
	v_mov_b32_e32 v74, v0
	v_mov_b32_e32 v75, v0
	v_mov_b32_e32 v234, v0
	v_mov_b32_e32 v70, v0
	v_lshlrev_b32_e32 v22, 2, v10
	v_add_lshl_u32 v23, s66, v10, 1
	v_lshl_add_u32 v21, v20, 11, v23
	v_lshl_add_u32 v20, v20, 13, v22
	v_lshl_add_u32 v27, v26, 11, v23
	v_lshl_add_u32 v26, v26, 13, v22
	v_lshl_add_u32 v29, v28, 11, v23
	v_lshl_add_u32 v28, v28, 13, v22
	v_lshl_add_u32 v31, v30, 11, v23
	v_lshl_add_u32 v30, v30, 13, v22
	v_lshl_add_u32 v33, v32, 11, v23
	v_lshl_add_u32 v32, v32, 13, v22
	v_lshl_add_u32 v35, v34, 11, v23
	v_lshl_add_u32 v34, v34, 13, v22
	v_lshl_add_u32 v37, v36, 11, v23
	v_lshl_add_u32 v36, v36, 13, v22
	v_lshl_add_u32 v39, v38, 11, v23
	v_lshl_add_u32 v38, v38, 13, v22
	v_lshl_add_u32 v41, v40, 11, v23
	v_lshl_add_u32 v40, v40, 13, v22
	v_lshl_add_u32 v43, v42, 11, v23
	v_lshl_add_u32 v42, v42, 13, v22
	v_lshl_add_u32 v45, v44, 11, v23
	v_lshl_add_u32 v44, v44, 13, v22
	v_lshl_add_u32 v47, v46, 11, v23
	v_lshl_add_u32 v46, v46, 13, v22
	v_lshl_add_u32 v49, v48, 11, v23
	v_lshl_add_u32 v48, v48, 13, v22
	v_lshl_add_u32 v51, v50, 11, v23
	v_lshl_add_u32 v50, v50, 13, v22
	v_lshl_add_u32 v53, v52, 11, v23
	v_lshl_add_u32 v52, v52, 13, v22
	v_lshl_add_u32 v55, v54, 11, v23
	v_lshl_add_u32 v54, v54, 13, v22
	s_branch .LBB0_54

; #define LAS __attribute__((address_space(3)))
; #define GAS __attribute__((address_space(1)))
; __device__ __forceinline__ bf16_t f2bf(float x) { return (bf16_t)(cvt_pk_bf16(x, x) & 0xffffu); }
; __device__ __forceinline__ float bf2f(bf16_t v) { return __uint_as_float((unsigned)v << 16); }
; __device__ __forceinline__ u32x4 pack8(const float* v) { u32x4 w; w.x = cvt_pk_bf16(v[0], v[1]); w.y = cvt_pk_bf16(v[2], v[3]); w.z = cvt_pk_bf16(v[4], v[5]); w.w = cvt_pk_bf16(v[6], v[7]); return w; }
; template <int DK, int DVS, bool RET> ...
;     ...
;                 for (int j = 0; j < 4; ++j) STB[(tv * 16 + quad * 4 + j) * LK + (kt0 + t) * 16 + l16] = f2bf(st[t][j]);
;             { const int p = tid >> 3, vg = tid & 7; const long row = R0 + (dir ? 63 - p : p); vraw = *(const GAS vvec_t*)(Vg + row * ldv + vcol0 + vg * VPT); }
;             float bl;
;             if constexpr (RET) {
;                 static_assert(!RET || DK == 256, "retention prep: 64 x 256 = 2048 eight-wide items, four per thread");
;                 bl = 64.f * lg;
; #pragma unroll
;                 for (int j = 0; j < 4; ++j) { const int it = tid + 512 * j, p = it & 63, k0 = (it >> 6) * 8; const float bb = (float)(p + 1) * lg;
;                     const float eq = __expf(bb), ek = __expf(-bb); float a[8], c[8];
; #pragma unroll
;                     for (int e = 0; e < 8; ++e) { a[e] = bf2f((bf16_t)qv[j][e]) * eq; c[e] = bf2f((bf16_t)kv[j][e]) * ek; }
;                     *(LAS u32x4*)(QD + p * LK + k0) = pack8(a); *(LAS u32x4*)(KD + p * LK + k0) = pack8(c); }
;             } else {
;                 float c = 0.f;
; #pragma unroll
;                 for (int i = 0; i < PPT; ++i) c += lc[i];
;                 TOT[pg * 128 + kx] = c;
;                 GLA_BAR();
;                 float off = 0.f; bl = 0.f;
; #pragma unroll
;                 for (int g = 0; g < NPG; ++g) { const float t = TOT[g * 128 + kx]; if (g < pg) off += t; bl += t; }
;                 float bb = off;
; #pragma unroll
;                 for (int i = 0; i < PPT; ++i) { const int p = pg * PPT + i;
;                     const float qf = bf2f(qr[i]), kf = 1.f - __expf(lc[i]); bb += lc[i];
;                     QD[p * LK + kx] = f2bf(qf * __expf(bb)); KD[p * LK + kx] = f2bf(kf * __expf(-bb)); }
.LBB0_54:
	v_cvt_pk_bf16_f32 v71, v71, s0
	s_waitcnt lgkmcnt(0)
	s_barrier
	ds_write_b16 v213, v71 offset:272
	v_cvt_pk_bf16_f32 v71, v72, s0
	s_waitcnt vmcnt(0)
	v_add_f32_e32 v72, 0, v132
	v_add_f32_e32 v72, v134, v72
	v_add_f32_e32 v72, v136, v72
	v_add_f32_e32 v72, v138, v72
	v_add_f32_e32 v72, v140, v72
	s_cmp_gt_u32 s36, 3
	v_add_f32_e32 v72, v142, v72
	s_cselect_b32 s40, 0x47, 3
	v_add_f32_e32 v72, v147, v72
	s_add_i32 s40, s40, s41
	v_add_f32_e32 v72, v151, v72
	s_and_b64 s[44:45], s[30:31], exec
	v_add_f32_e32 v72, v210, v72
	s_cselect_b32 s40, s36, s40
	v_add_f32_e32 v72, v220, v72
	s_lshl_b32 s40, s40, 6
	ds_write_b16 v213, v71 offset:544
	v_cvt_pk_bf16_f32 v71, v73, s0
	v_add_f32_e32 v72, v222, v72
	s_ashr_i32 s45, s40, 31
	ds_write_b16 v213, v71 offset:816
	v_cvt_pk_bf16_f32 v71, v74, s0
	v_add_f32_e32 v72, v224, v72
	ds_write_b16 v214, v71
	v_cvt_pk_bf16_f32 v71, v75, s0
	s_add_u32 s44, s42, s40
	v_add_f32_e32 v72, v226, v72
	ds_write_b16 v214, v71 offset:272
	v_cvt_pk_bf16_f32 v71, v234, s0
	v_cvt_pk_bf16_f32 v70, v70, s0
	s_addc_u32 s45, s43, s45
	v_add_f32_e32 v72, v228, v72
	ds_write_b16 v214, v71 offset:544
	ds_write_b16 v214, v70 offset:816
	v_lshl_add_u64 v[70:71], s[44:45], 0, v[56:57]
	v_add_f32_e32 v72, v230, v72
	v_cvt_pk_bf16_f32 v110, v0, s0
	v_lshlrev_b64 v[70:71], 11, v[70:71]
	v_add_f32_e32 v72, v232, v72
	ds_write_b16 v213, v110
	v_lshl_add_u64 v[70:71], v[58:59], 0, v[70:71]
	ds_write_b32 v152, v72
	global_load_dwordx2 v[70:71], v[70:71], off
	s_waitcnt lgkmcnt(0)
	s_barrier
	s_add_i32 s39, s36, 1
	s_min_i32 s39, s39, 0x43
	s_cmp_gt_u32 s39, 3
	s_cselect_b32 s38, 0x47, 3
	s_sub_i32 s38, s38, s39
	s_and_b64 s[54:55], s[30:31], exec
	s_cselect_b32 s38, s39, s38
	s_lshl_b32 s38, s38, 6
	s_ashr_i32 s39, s38, 31
	s_add_u32 s54, s42, s38
	s_addc_u32 s55, s43, s39
	s_lshl_b64 s[38:39], s[54:55], 11
	s_add_u32 s38, s38, s90
	s_addc_u32 s39, s39, s91
	s_lshl_b64 s[54:55], s[54:55], 13
	s_add_u32 s54, s54, s64
	s_addc_u32 s55, s55, s65
	ds_read2st64_b32 v[72:73], v153 offset1:2
	v_mul_f32_e32 v112, 0x3fb8aa3b, v132
	v_exp_f32_e32 v112, v112
	s_waitcnt lgkmcnt(0)
	v_add_f32_e32 v72, 0, v72
	v_cndmask_b32_e64 v74, 0, v72, s[6:7]
	v_add_f32_e32 v75, v73, v74
	v_cndmask_b32_e64 v110, v74, v75, s[8:9]
	ds_read2st64_b32 v[74:75], v153 offset0:4 offset1:6
	v_sub_f32_e32 v112, 1.0, v112
	s_waitcnt lgkmcnt(0)
	v_add_f32_e32 v111, v74, v110
	v_cndmask_b32_e64 v110, v110, v111, s[10:11]
	v_add_f32_e32 v111, v75, v110
	v_cndmask_b32_e64 v110, v110, v111, s[12:13]
	v_add_f32_e32 v110, v132, v110
	v_mul_f32_e32 v113, 0x3fb8aa3b, v110
	v_exp_f32_e32 v113, v113
	v_lshlrev_b32_e32 v111, 16, v133
	global_load_dword v132, v20, s[54:55]
	global_load_ushort v133, v21, s[38:39]
	v_mul_f32_e32 v111, v113, v111
	v_cvt_pk_bf16_f32 v111, v111, s0
	ds_write_b16 v160, v111
	v_mul_f32_e32 v111, 0xbfb8aa3b, v110
	v_exp_f32_e32 v111, v111
	v_add_f32_e32 v110, v134, v110
	v_mul_f32_e32 v113, 0x3fb8aa3b, v110
	v_exp_f32_e32 v113, v113
	v_mul_f32_e32 v111, v112, v111
	v_cvt_pk_bf16_f32 v111, v111, s0
	ds_write_b16 v161, v111
	v_lshlrev_b32_e32 v111, 16, v135
	v_mul_f32_e32 v111, v113, v111
	v_mul_f32_e32 v112, 0x3fb8aa3b, v134
	global_load_dword v134, v26, s[54:55]
	global_load_ushort v135, v27, s[38:39]
	v_cvt_pk_bf16_f32 v111, v111, s0
	v_exp_f32_e32 v112, v112
	ds_write_b16 v163, v111
	v_mul_f32_e32 v111, 0xbfb8aa3b, v110
	v_exp_f32_e32 v111, v111
	v_add_f32_e32 v110, v136, v110
	v_mul_f32_e32 v113, 0x3fb8aa3b, v110
	v_sub_f32_e32 v112, 1.0, v112
	v_exp_f32_e32 v113, v113
	v_mul_f32_e32 v111, v112, v111
	v_cvt_pk_bf16_f32 v111, v111, s0
	ds_write_b16 v164, v111
	v_lshlrev_b32_e32 v111, 16, v137
	v_mul_f32_e32 v111, v113, v111
	v_mul_f32_e32 v112, 0x3fb8aa3b, v136
	global_load_dword v136, v28, s[54:55]
	global_load_ushort v137, v29, s[38:39]
	v_cvt_pk_bf16_f32 v111, v111, s0
	v_exp_f32_e32 v112, v112
	ds_write_b16 v165, v111
	v_mul_f32_e32 v111, 0xbfb8aa3b, v110
	v_exp_f32_e32 v111, v111
	v_add_f32_e32 v110, v138, v110
	v_mul_f32_e32 v113, 0x3fb8aa3b, v110
	v_sub_f32_e32 v112, 1.0, v112
	v_exp_f32_e32 v113, v113
	v_mul_f32_e32 v111, v112, v111
	v_cvt_pk_bf16_f32 v111, v111, s0
	ds_write_b16 v166, v111
	v_lshlrev_b32_e32 v111, 16, v139
	v_mul_f32_e32 v111, v113, v111
	v_mul_f32_e32 v112, 0x3fb8aa3b, v138
	global_load_dword v138, v30, s[54:55]
	global_load_ushort v139, v31, s[38:39]
	v_cvt_pk_bf16_f32 v111, v111, s0
	v_exp_f32_e32 v112, v112
	ds_write_b16 v167, v111
	v_mul_f32_e32 v111, 0xbfb8aa3b, v110
	v_exp_f32_e32 v111, v111
	v_add_f32_e32 v110, v140, v110
	v_mul_f32_e32 v113, 0x3fb8aa3b, v110
	v_sub_f32_e32 v112, 1.0, v112
	v_exp_f32_e32 v113, v113
	v_mul_f32_e32 v111, v112, v111
	v_cvt_pk_bf16_f32 v111, v111, s0
	ds_write_b16 v168, v111
	v_lshlrev_b32_e32 v111, 16, v141
	v_mul_f32_e32 v111, v113, v111
	v_mul_f32_e32 v112, 0x3fb8aa3b, v140
	global_load_dword v140, v32, s[54:55]
	global_load_ushort v141, v33, s[38:39]
	v_cvt_pk_bf16_f32 v111, v111, s0
	v_exp_f32_e32 v112, v112
	ds_write_b16 v169, v111
	v_mul_f32_e32 v111, 0xbfb8aa3b, v110
	v_exp_f32_e32 v111, v111
	v_add_f32_e32 v110, v142, v110
	v_mul_f32_e32 v113, 0x3fb8aa3b, v110
	v_sub_f32_e32 v112, 1.0, v112
	v_exp_f32_e32 v113, v113
	v_mul_f32_e32 v111, v112, v111
	v_cvt_pk_bf16_f32 v111, v111, s0
	ds_write_b16 v170, v111
	v_lshlrev_b32_e32 v111, 16, v143
	v_mul_f32_e32 v111, v113, v111
	v_mul_f32_e32 v112, 0x3fb8aa3b, v142
	global_load_dword v142, v34, s[54:55]
	global_load_ushort v143, v35, s[38:39]
	v_cvt_pk_bf16_f32 v111, v111, s0
	v_exp_f32_e32 v112, v112
	ds_write_b16 v171, v111
	v_mul_f32_e32 v111, 0xbfb8aa3b, v110
	v_exp_f32_e32 v111, v111
	v_add_f32_e32 v110, v147, v110
; #define LAS __attribute__((address_space(3)))
; __device__ __forceinline__ bf16_t f2bf(float x) { return (bf16_t)(cvt_pk_bf16(x, x) & 0xffffu); }
; __device__ __forceinline__ float bf2f(bf16_t v) { return __uint_as_float((unsigned)v << 16); }
; template <int DK, int DVS, bool RET> ...
;     ...
;                 float bb = off;
; #pragma unroll
;                 for (int i = 0; i < PPT; ++i) { const int p = pg * PPT + i;
;                     const float qf = bf2f(qr[i]), kf = 1.f - __expf(lc[i]); bb += lc[i];
;                     QD[p * LK + kx] = f2bf(qf * __expf(bb)); KD[p * LK + kx] = f2bf(kf * __expf(-bb)); }
;             }
;             if (pg == 0) EL[kx] = __expf(bl);
;             { const int p = tid >> 3, vg = tid & 7; *(LAS vvec_t*)(VI + p * LV + vg * VPT) = vraw; }
;         }
;         if (step + 1 < 68) GLA_LOAD(step + 1);
	v_mul_f32_e32 v113, 0x3fb8aa3b, v110
	v_sub_f32_e32 v112, 1.0, v112
	v_exp_f32_e32 v113, v113
	v_mul_f32_e32 v111, v112, v111
	v_cvt_pk_bf16_f32 v111, v111, s0
	ds_write_b16 v172, v111
	v_lshlrev_b32_e32 v111, 16, v150
	v_mul_f32_e32 v111, v113, v111
	v_mul_f32_e32 v112, 0x3fb8aa3b, v147
	global_load_dword v147, v36, s[54:55]
	global_load_ushort v150, v37, s[38:39]
	v_cvt_pk_bf16_f32 v111, v111, s0
	v_exp_f32_e32 v112, v112
	ds_write_b16 v173, v111
	v_mul_f32_e32 v111, 0xbfb8aa3b, v110
	v_exp_f32_e32 v111, v111
	v_add_f32_e32 v110, v151, v110
	v_mul_f32_e32 v113, 0x3fb8aa3b, v110
	v_sub_f32_e32 v112, 1.0, v112
	v_exp_f32_e32 v113, v113
	v_mul_f32_e32 v111, v112, v111
	v_cvt_pk_bf16_f32 v111, v111, s0
	ds_write_b16 v174, v111
	v_lshlrev_b32_e32 v111, 16, v162
	v_mul_f32_e32 v111, v113, v111
	v_mul_f32_e32 v112, 0x3fb8aa3b, v151
	global_load_dword v151, v38, s[54:55]
	global_load_ushort v162, v39, s[38:39]
	v_cvt_pk_bf16_f32 v111, v111, s0
	v_exp_f32_e32 v112, v112
	ds_write_b16 v175, v111
	v_mul_f32_e32 v111, 0xbfb8aa3b, v110
	v_exp_f32_e32 v111, v111
	v_add_f32_e32 v110, v210, v110
	v_mul_f32_e32 v113, 0x3fb8aa3b, v110
	v_sub_f32_e32 v112, 1.0, v112
	v_exp_f32_e32 v113, v113
	v_mul_f32_e32 v111, v112, v111
	v_cvt_pk_bf16_f32 v111, v111, s0
	ds_write_b16 v176, v111
	v_lshlrev_b32_e32 v111, 16, v217
	v_mul_f32_e32 v111, v113, v111
	v_mul_f32_e32 v112, 0x3fb8aa3b, v210
	global_load_dword v210, v40, s[54:55]
	global_load_ushort v217, v41, s[38:39]
	v_cvt_pk_bf16_f32 v111, v111, s0
	v_exp_f32_e32 v112, v112
	ds_write_b16 v177, v111
	v_mul_f32_e32 v111, 0xbfb8aa3b, v110
	v_exp_f32_e32 v111, v111
	v_add_f32_e32 v110, v220, v110
	v_mul_f32_e32 v113, 0x3fb8aa3b, v110
	v_sub_f32_e32 v112, 1.0, v112
	v_exp_f32_e32 v113, v113
	v_mul_f32_e32 v111, v112, v111
	v_cvt_pk_bf16_f32 v111, v111, s0
	ds_write_b16 v178, v111
	v_lshlrev_b32_e32 v111, 16, v221
	v_mul_f32_e32 v111, v113, v111
	v_mul_f32_e32 v112, 0x3fb8aa3b, v220
	global_load_dword v220, v42, s[54:55]
	global_load_ushort v221, v43, s[38:39]
	v_cvt_pk_bf16_f32 v111, v111, s0
	v_exp_f32_e32 v112, v112
	ds_write_b16 v179, v111
	v_mul_f32_e32 v111, 0xbfb8aa3b, v110
	v_exp_f32_e32 v111, v111
	v_add_f32_e32 v110, v222, v110
	v_mul_f32_e32 v113, 0x3fb8aa3b, v110
	v_sub_f32_e32 v112, 1.0, v112
	v_exp_f32_e32 v113, v113
	v_mul_f32_e32 v111, v112, v111
	v_cvt_pk_bf16_f32 v111, v111, s0
	ds_write_b16 v180, v111
	v_lshlrev_b32_e32 v111, 16, v223
	v_mul_f32_e32 v111, v113, v111
	v_mul_f32_e32 v112, 0x3fb8aa3b, v222
	global_load_dword v222, v44, s[54:55]
	global_load_ushort v223, v45, s[38:39]
	v_cvt_pk_bf16_f32 v111, v111, s0
	v_exp_f32_e32 v112, v112
	ds_write_b16 v181, v111
	v_mul_f32_e32 v111, 0xbfb8aa3b, v110
	v_exp_f32_e32 v111, v111
	v_add_f32_e32 v110, v224, v110
	v_mul_f32_e32 v113, 0x3fb8aa3b, v110
	v_sub_f32_e32 v112, 1.0, v112
	v_exp_f32_e32 v113, v113
	v_mul_f32_e32 v111, v112, v111
	v_cvt_pk_bf16_f32 v111, v111, s0
	ds_write_b16 v182, v111
	v_lshlrev_b32_e32 v111, 16, v225
	v_mul_f32_e32 v111, v113, v111
	v_mul_f32_e32 v112, 0x3fb8aa3b, v224
	global_load_dword v224, v46, s[54:55]
	global_load_ushort v225, v47, s[38:39]
	v_cvt_pk_bf16_f32 v111, v111, s0
	v_exp_f32_e32 v112, v112
	ds_write_b16 v183, v111
	v_mul_f32_e32 v111, 0xbfb8aa3b, v110
	v_exp_f32_e32 v111, v111
	v_add_f32_e32 v110, v226, v110
	v_mul_f32_e32 v113, 0x3fb8aa3b, v110
	v_sub_f32_e32 v112, 1.0, v112
	v_exp_f32_e32 v113, v113
	v_mul_f32_e32 v111, v112, v111
	v_cvt_pk_bf16_f32 v111, v111, s0
	ds_write_b16 v184, v111
	v_lshlrev_b32_e32 v111, 16, v227
	v_mul_f32_e32 v111, v113, v111
	v_mul_f32_e32 v112, 0x3fb8aa3b, v226
	global_load_dword v226, v48, s[54:55]
	global_load_ushort v227, v49, s[38:39]
	v_cvt_pk_bf16_f32 v111, v111, s0
	v_exp_f32_e32 v112, v112
	ds_write_b16 v185, v111
	v_mul_f32_e32 v111, 0xbfb8aa3b, v110
	v_exp_f32_e32 v111, v111
	v_add_f32_e32 v110, v228, v110
	v_mul_f32_e32 v113, 0x3fb8aa3b, v110
	v_sub_f32_e32 v112, 1.0, v112
	v_exp_f32_e32 v113, v113
	v_mul_f32_e32 v111, v112, v111
	v_cvt_pk_bf16_f32 v111, v111, s0
	ds_write_b16 v199, v111
	v_lshlrev_b32_e32 v111, 16, v229
	v_mul_f32_e32 v111, v113, v111
	v_mul_f32_e32 v112, 0x3fb8aa3b, v228
	global_load_dword v228, v50, s[54:55]
	global_load_ushort v229, v51, s[38:39]
	v_cvt_pk_bf16_f32 v111, v111, s0
	v_exp_f32_e32 v112, v112
	ds_write_b16 v200, v111
	v_mul_f32_e32 v111, 0xbfb8aa3b, v110
	v_exp_f32_e32 v111, v111
	v_add_f32_e32 v110, v230, v110
	v_mul_f32_e32 v113, 0x3fb8aa3b, v110
	v_sub_f32_e32 v112, 1.0, v112
	v_exp_f32_e32 v113, v113
	v_mul_f32_e32 v111, v112, v111
	v_cvt_pk_bf16_f32 v111, v111, s0
	ds_write_b16 v201, v111
	v_lshlrev_b32_e32 v111, 16, v231
	v_mul_f32_e32 v111, v113, v111
	v_mul_f32_e32 v112, 0x3fb8aa3b, v230
	global_load_dword v230, v52, s[54:55]
	global_load_ushort v231, v53, s[38:39]
	v_cvt_pk_bf16_f32 v111, v111, s0
	v_exp_f32_e32 v112, v112
	ds_write_b16 v202, v111
	v_mul_f32_e32 v111, 0xbfb8aa3b, v110
	v_exp_f32_e32 v111, v111
	v_sub_f32_e32 v112, 1.0, v112
	v_add_f32_e32 v110, v232, v110
	v_mul_f32_e32 v113, 0x3fb8aa3b, v110
	v_mul_f32_e32 v111, v112, v111
	v_mul_f32_e32 v112, 0x3fb8aa3b, v232
	v_exp_f32_e32 v112, v112
	v_mul_f32_e32 v110, 0xbfb8aa3b, v110
	v_exp_f32_e32 v113, v113
	v_exp_f32_e32 v110, v110
	v_cvt_pk_bf16_f32 v111, v111, s0
	ds_write_b16 v203, v111
	v_lshlrev_b32_e32 v111, 16, v233
	global_load_dword v232, v54, s[54:55]
	global_load_ushort v233, v55, s[38:39]
	v_sub_f32_e32 v112, 1.0, v112
	v_mul_f32_e32 v111, v113, v111
	v_mul_f32_e32 v110, v112, v110
	v_cvt_pk_bf16_f32 v111, v111, s0
	v_cvt_pk_bf16_f32 v110, v110, s0
	ds_write_b16 v204, v111
	ds_write_b16 v205, v110
	s_and_saveexec_b64 s[46:47], vcc
	s_cbranch_execz .LBB0_56
	v_add_f32_e32 v72, v72, v73
	v_add_f32_e32 v72, v72, v74
	v_add_f32_e32 v72, v72, v75
	v_mul_f32_e32 v72, 0x3fb8aa3b, v72
	v_exp_f32_e32 v72, v72
	ds_write_b32 v154, v72
.LBB0_56:
	s_or_b64 exec, exec, s[46:47]
	s_add_i32 s40, s36, 1
	s_cmpk_eq_i32 s41, 0xffbd
	s_waitcnt vmcnt(32)
	ds_write_b64 v155, v[70:71]
	s_branch .LBB0_53
